# mixer-phase queues: the GLA workgroups (bx < 32), which join late, also start on the decode list
# speedup vs baseline: 1.0121x; 1.0077x over previous
; DEV int lane_id() { int l; asm volatile("v_mbcnt_lo_u32_b32 %0, -1, 0\n\tv_mbcnt_hi_u32_b32 %0, -1, %0" : "=v"(l)); return l; }
; #define LAS __attribute__((address_space(3)))
; __global__ void __launch_bounds__(512, 2) mk_fwd(MKArgs args) {
;     ...
;             { volatile LAS unsigned* LQ = (volatile LAS unsigned*)(ldsl + LDSCTL_OFF + 512);
;               unsigned* qd = (unsigned*)(ws + WS_CTL) + CW_Q3 + 128 * l; unsigned* qa = qd + 64;
;               const bool dclass = (bx >> 3) == 19 || (bx >> 3) == 27;
;               constexpr unsigned ND = SB * NSPLIT, NA = NB * MH * 8 + M / 256;
;               for (;;) {
;                   if (wave_s == 0 && lane_id() == 0) { unsigned kind = 2u, idx = 0u;
;                       if (dclass) { idx = __hip_atomic_fetch_add(qd, 1u, __ATOMIC_RELAXED, __HIP_MEMORY_SCOPE_AGENT); if (idx < ND) kind = 0u; else { idx = __hip_atomic_fetch_add(qa, 1u, __ATOMIC_RELAXED, __HIP_MEMORY_SCOPE_AGENT); if (idx < NA) kind = 1u; } }
;                       else { idx = __hip_atomic_fetch_add(qa, 1u, __ATOMIC_RELAXED, __HIP_MEMORY_SCOPE_AGENT); if (idx < NA) kind = 1u; else { idx = __hip_atomic_fetch_add(qd, 1u, __ATOMIC_RELAXED, __HIP_MEMORY_SCOPE_AGENT); if (idx < ND) kind = 0u; } }
;                       LQ[0] = kind; LQ[1] = idx; }
.LBB0_1240:
	s_waitcnt lgkmcnt(0)
	v_readlane_b32 s10, v255, 0
	v_readlane_b32 s14, v254, 1
	s_lshl_b32 s4, s10, 11
	v_readlane_b32 s15, v254, 2
	v_readlane_b32 s11, v255, 1
	s_barrier
	v_writelane_b32 v255, s4, 31
	v_readlane_b32 s4, v254, 9
	s_lshl_b32 s6, s10, 12
	s_load_dwordx2 s[22:23], s[14:15], 0x120
	v_readlane_b32 s5, v254, 10
	v_writelane_b32 v255, s6, 33
	s_load_dword s4, s[4:5], 0x0
	v_readlane_b32 s5, v254, 0
	v_writelane_b32 v255, s7, 34
	s_mov_b32 s6, s57
	s_waitcnt lgkmcnt(0)
	s_lshl_b64 s[0:1], s[10:11], 14
	s_lshl_b64 s[2:3], s[10:11], 20
	s_add_i32 s50, s6, 0
	v_readlane_b32 s4, v254, 52
	s_add_u32 s4, s22, s4
	s_addc_u32 s6, s23, 0
	s_add_i32 s51, s50, 0x20200
	s_lshl_b64 s[8:9], s[38:39], 2
	s_add_u32 s7, s22, s8
	v_writelane_b32 v255, s8, 40
	s_mul_hi_u32 s26, s10, 0x1400
	s_mul_i32 s27, s10, 0x1400
	v_writelane_b32 v255, s9, 41
	s_addc_u32 s8, s23, s9
	s_add_u32 s12, s7, 0xa6040
	s_addc_u32 s13, s8, 0
	v_writelane_b32 v255, s12, 26
	s_nop 1
	v_writelane_b32 v255, s13, 27
	s_add_u32 s12, s7, 0xa6140
	s_addc_u32 s13, s8, 0
	s_sub_u32 s5, s5, 32
	s_cmpk_lt_u32 s5, 0x60
	s_cselect_b64 s[8:9], -1, 0
	s_add_i32 s52, s50, 0x20204
	s_add_i32 s53, s50, 0x17a00
	s_add_i32 s62, s50, 0x19e00
	s_add_u32 s63, s22, 0x1a798300
	s_addc_u32 s72, s23, 0
	s_add_i32 s73, s50, 0x15000
	s_add_i32 s78, s50, 0x1a000
	s_add_i32 s5, s50, 0x18e00
	s_add_u32 s2, s22, s2
	s_addc_u32 s3, s23, s3
	s_add_u32 s88, s2, 0x1a7d5300
	s_addc_u32 s89, s3, 0
	s_add_u32 s0, s22, s0
	s_addc_u32 s1, s23, s1
	s_add_u32 s40, s0, 0x1abd5300
	s_addc_u32 s41, s1, 0
	v_writelane_b32 v254, s5, 50
	s_add_u32 s0, s22, 0x9c400
	v_writelane_b32 v254, s0, 62
	s_addc_u32 s0, s23, 0
	v_writelane_b32 v254, s0, 60
	s_add_u32 s0, s22, 0x1a7c0300
	s_addc_u32 s37, s23, 0
	v_writelane_b32 v254, s0, 54
	s_add_u32 s0, s22, 0x1a7c5500
	v_writelane_b32 v254, s0, 58
	v_writelane_b32 v255, s12, 29
	v_readlane_b32 s0, v254, 47
	v_readlane_b32 s1, v254, 48
	v_writelane_b32 v255, s13, 30
	v_writelane_b32 v255, s8, 6
	s_addc_u32 s36, s23, 0
	s_lshl_b64 s[2:3], s[0:1], 2
	v_writelane_b32 v255, s9, 7
	s_add_u32 s0, s22, s2
	v_writelane_b32 v255, s2, 42
	s_addc_u32 s1, s23, s3
	s_add_u32 s0, s0, 0xce800
	v_writelane_b32 v255, s3, 43
	s_addc_u32 s1, s1, 0
	v_writelane_b32 v255, s0, 44
	s_nop 1
	v_writelane_b32 v255, s1, 45
	s_add_u32 s0, s22, 0xee58100
	v_writelane_b32 v255, s0, 10
	s_addc_u32 s0, s23, 0
	v_writelane_b32 v255, s0, 12
	s_add_u32 s0, s22, 0xfe58100
	v_writelane_b32 v254, s0, 49
	s_addc_u32 s0, s23, 0
	v_writelane_b32 v255, s0, 8
	s_add_u32 s0, s22, 0x10658100
	v_writelane_b32 v255, s0, 32
	s_addc_u32 s0, s23, 0
	v_writelane_b32 v255, s0, 18
	s_add_u32 s0, s22, 0x11658100
	v_writelane_b32 v255, s0, 20
	s_addc_u32 s0, s23, 0
	v_writelane_b32 v255, s0, 22
	s_add_u32 s0, s22, 0x11758100
	v_writelane_b32 v255, s0, 24
	s_addc_u32 s0, s23, 0
	v_writelane_b32 v255, s0, 28
	s_add_u32 s0, s22, 0xbc800
	v_writelane_b32 v255, s0, 14
	s_addc_u32 s0, s23, 0
	s_add_u32 s60, s22, 0x12758100
	s_addc_u32 s61, s23, 0
	s_add_u32 s64, s4, 0x4e0000
	s_addc_u32 s65, s6, 0
	s_add_u32 s42, s22, 0x12f58100
	s_addc_u32 s43, s23, 0
	s_add_i32 s38, s50, 0x10000
	v_writelane_b32 v255, s0, 46
	s_add_u32 s0, s4, 0x4f0000
	s_addc_u32 s1, s6, 0
	s_add_i32 s39, s50, 0x14000
	s_add_u32 s20, s4, 0x4e0080
	s_addc_u32 s21, s6, 0
	s_add_i32 s24, s50, 0x18000
	s_add_u32 s70, s4, 0x4f0080
	s_addc_u32 s71, s6, 0
	s_add_i32 s25, s50, 0x1c000
	s_add_u32 s80, s4, 0x4e0100
	s_addc_u32 s81, s6, 0
	s_add_u32 s2, s4, 0x4f0100
	s_addc_u32 s3, s6, 0
	s_add_u32 s58, s4, 0x4e0180
	s_addc_u32 s59, s6, 0
	s_add_u32 s54, s4, 0x4f0180
	s_addc_u32 s55, s6, 0
	s_branch .LBB0_1246
